# grid barriers 2-14: hand-written thread-0 section, all workgroups poll the cross-XCD arrival counter directly (no TOPGEN/XGEN relay, no divisions)
# speedup vs baseline: 1.0089x; 1.0059x over previous
.LBB0_233:
	s_waitcnt vmcnt(0)
	s_waitcnt vmcnt(0)
	s_barrier
	s_and_saveexec_b64 s[0:1], s[10:11]
	s_cbranch_execz .LBB0_285
	v_mov_b32_e32 v0, 0x23fc0
	s_waitcnt vmcnt(0) expcnt(0) lgkmcnt(0)
	ds_read_b64 v[4:5], v0
	s_lshl_b32 s2, s19, 8
	s_add_u32 s2, s42, s2
	s_addc_u32 s3, s43, 0
	v_mov_b32_e32 v1, 0x1000
	v_mov_b32_e32 v2, 1
	global_atomic_add v1, v1, v2, s[2:3] offset:1024 sc0
	s_waitcnt lgkmcnt(0)
	v_readfirstlane_b32 s8, v4
	v_readfirstlane_b32 s9, v5
	s_mul_i32 s72, s8, 2
	s_mul_i32 s73, s9, 2
	s_waitcnt vmcnt(0)
	v_readfirstlane_b32 s74, v1
	s_add_i32 s74, s74, 1
	s_cmp_lg_u32 s74, s72
	s_cbranch_scc1 .Lgb1_poll
	buffer_wbl2 sc1
	s_waitcnt vmcnt(0)
	v_mov_b32_e32 v1, 0x3323000
	global_atomic_add v1, v2, s[44:45] offset:1024
.Lgb1_poll:
	v_mov_b32_e32 v1, 0x3323000
	s_mov_b32 s77, 0
.Lgb1_spin:
	global_load_dword v4, v1, s[44:45] offset:1024 sc1
	s_waitcnt vmcnt(0)
	v_readfirstlane_b32 s78, v4
	s_cmp_ge_u32 s78, s73
	s_cbranch_scc1 .Lgb1_rel
	s_sleep 1
	s_add_i32 s77, s77, 1
	s_cmp_lt_u32 s77, 0x40000
	s_cbranch_scc1 .Lgb1_spin
.Lgb1_rel:
	buffer_inv sc1
	s_waitcnt vmcnt(0)

.LBB0_317:
	s_or_b64 exec, exec, s[0:1]
	s_waitcnt vmcnt(0)
	s_waitcnt lgkmcnt(0)
	s_barrier
	s_and_saveexec_b64 s[0:1], s[10:11]
	s_cbranch_execz .LBB0_369
	v_mov_b32_e32 v0, 0x23fc0
	s_waitcnt vmcnt(0) expcnt(0) lgkmcnt(0)
	ds_read_b64 v[4:5], v0
	s_lshl_b32 s2, s19, 8
	s_add_u32 s2, s42, s2
	s_addc_u32 s3, s43, 0
	v_mov_b32_e32 v1, 0x1000
	v_mov_b32_e32 v2, 1
	global_atomic_add v1, v1, v2, s[2:3] offset:1024 sc0
	s_waitcnt lgkmcnt(0)
	v_readfirstlane_b32 s8, v4
	v_readfirstlane_b32 s9, v5
	s_mul_i32 s72, s8, 3
	s_mul_i32 s73, s9, 3
	s_waitcnt vmcnt(0)
	v_readfirstlane_b32 s74, v1
	s_add_i32 s74, s74, 1
	s_cmp_lg_u32 s74, s72
	s_cbranch_scc1 .Lgb2_poll
	buffer_wbl2 sc1
	s_waitcnt vmcnt(0)
	v_mov_b32_e32 v1, 0x3323000
	global_atomic_add v1, v2, s[44:45] offset:1024

.LBB0_593:
	s_waitcnt vmcnt(0)
	s_waitcnt vmcnt(0)
	s_barrier
	s_and_saveexec_b64 s[0:1], s[10:11]
	s_cbranch_execz .LBB0_645
	v_mov_b32_e32 v0, 0x23fc0
	s_waitcnt vmcnt(0) expcnt(0) lgkmcnt(0)
	ds_read_b64 v[4:5], v0
	s_lshl_b32 s2, s19, 8
	s_add_u32 s2, s42, s2
	s_addc_u32 s3, s43, 0
	v_mov_b32_e32 v1, 0x1000
	v_mov_b32_e32 v2, 1
	global_atomic_add v1, v1, v2, s[2:3] offset:1024 sc0
	s_waitcnt lgkmcnt(0)
	v_readfirstlane_b32 s8, v4
	v_readfirstlane_b32 s9, v5
	s_mul_i32 s72, s8, 4
	s_mul_i32 s73, s9, 4
	s_waitcnt vmcnt(0)
	v_readfirstlane_b32 s74, v1
	s_add_i32 s74, s74, 1
	s_cmp_lg_u32 s74, s72
	s_cbranch_scc1 .Lgb3_poll
	buffer_wbl2 sc1
	s_waitcnt vmcnt(0)
	v_mov_b32_e32 v1, 0x3323000
	global_atomic_add v1, v2, s[44:45] offset:1024

.LBB0_667:
	s_waitcnt vmcnt(0)
	s_waitcnt lgkmcnt(0)
	s_barrier
	s_and_saveexec_b64 s[0:1], s[10:11]
	s_cbranch_execz .LBB0_719
	v_mov_b32_e32 v0, 0x23fc0
	s_waitcnt vmcnt(0) expcnt(0) lgkmcnt(0)
	ds_read_b64 v[4:5], v0
	s_lshl_b32 s2, s19, 8
	s_add_u32 s2, s42, s2
	s_addc_u32 s3, s43, 0
	v_mov_b32_e32 v1, 0x1000
	v_mov_b32_e32 v2, 1
	global_atomic_add v1, v1, v2, s[2:3] offset:1024 sc0
	s_waitcnt lgkmcnt(0)
	v_readfirstlane_b32 s8, v4
	v_readfirstlane_b32 s9, v5
	s_mul_i32 s72, s8, 5
	s_mul_i32 s73, s9, 5
	s_waitcnt vmcnt(0)
	v_readfirstlane_b32 s74, v1
	s_add_i32 s74, s74, 1
	s_cmp_lg_u32 s74, s72
	s_cbranch_scc1 .Lgb4_poll
	buffer_wbl2 sc1
	s_waitcnt vmcnt(0)
	v_mov_b32_e32 v1, 0x3323000
	global_atomic_add v1, v2, s[44:45] offset:1024

.LBB0_975:
	s_setprio 0
	s_waitcnt vmcnt(0)
	s_barrier
	s_and_saveexec_b64 s[0:1], s[10:11]
	s_cbranch_execz .LBB0_1027
	v_mov_b32_e32 v0, 0x23fc0
	s_waitcnt vmcnt(0) expcnt(0) lgkmcnt(0)
	ds_read_b64 v[4:5], v0
	s_lshl_b32 s2, s19, 8
	s_add_u32 s2, s42, s2
	s_addc_u32 s3, s43, 0
	v_mov_b32_e32 v1, 0x1000
	v_mov_b32_e32 v2, 1
	global_atomic_add v1, v1, v2, s[2:3] offset:1024 sc0
	s_waitcnt lgkmcnt(0)
	v_readfirstlane_b32 s8, v4
	v_readfirstlane_b32 s9, v5
	s_mul_i32 s72, s8, 6
	s_mul_i32 s73, s9, 6
	s_waitcnt vmcnt(0)
	v_readfirstlane_b32 s74, v1
	s_add_i32 s74, s74, 1
	s_cmp_lg_u32 s74, s72
	s_cbranch_scc1 .Lgb5_poll
	buffer_wbl2 sc1
	s_waitcnt vmcnt(0)
	v_mov_b32_e32 v1, 0x3323000
	global_atomic_add v1, v2, s[44:45] offset:1024

.LBB0_1051:
	s_waitcnt vmcnt(0)
	s_barrier
	s_and_saveexec_b64 s[0:1], s[10:11]
	s_cbranch_execz .LBB0_1103
	v_mov_b32_e32 v0, 0x23fc0
	s_waitcnt vmcnt(0) expcnt(0) lgkmcnt(0)
	ds_read_b64 v[4:5], v0
	s_lshl_b32 s2, s19, 8
	s_add_u32 s2, s42, s2
	s_addc_u32 s3, s43, 0
	v_mov_b32_e32 v1, 0x1000
	v_mov_b32_e32 v2, 1
	global_atomic_add v1, v1, v2, s[2:3] offset:1024 sc0
	s_waitcnt lgkmcnt(0)
	v_readfirstlane_b32 s8, v4
	v_readfirstlane_b32 s9, v5
	s_mul_i32 s72, s8, 7
	s_mul_i32 s73, s9, 7
	s_waitcnt vmcnt(0)
	v_readfirstlane_b32 s74, v1
	s_add_i32 s74, s74, 1
	s_cmp_lg_u32 s74, s72
	s_cbranch_scc1 .Lgb6_poll
	buffer_wbl2 sc1
	s_waitcnt vmcnt(0)
	v_mov_b32_e32 v1, 0x3323000
	global_atomic_add v1, v2, s[44:45] offset:1024

.LBB0_1127:
	s_waitcnt vmcnt(0)
	s_barrier
	s_and_saveexec_b64 s[0:1], s[10:11]
	s_cbranch_execz .LBB0_1179
	v_mov_b32_e32 v0, 0x23fc0
	s_waitcnt vmcnt(0) expcnt(0) lgkmcnt(0)
	ds_read_b64 v[4:5], v0
	s_lshl_b32 s2, s19, 8
	s_add_u32 s2, s42, s2
	s_addc_u32 s3, s43, 0
	v_mov_b32_e32 v1, 0x1000
	v_mov_b32_e32 v2, 1
	global_atomic_add v1, v1, v2, s[2:3] offset:1024 sc0
	s_waitcnt lgkmcnt(0)
	v_readfirstlane_b32 s8, v4
	v_readfirstlane_b32 s9, v5
	s_mul_i32 s72, s8, 8
	s_mul_i32 s73, s9, 8
	s_waitcnt vmcnt(0)
	v_readfirstlane_b32 s74, v1
	s_add_i32 s74, s74, 1
	s_cmp_lg_u32 s74, s72
	s_cbranch_scc1 .Lgb7_poll
	buffer_wbl2 sc1
	s_waitcnt vmcnt(0)
	v_mov_b32_e32 v1, 0x3323000
	global_atomic_add v1, v2, s[44:45] offset:1024

.LBB0_1237:
	s_waitcnt vmcnt(0)
	s_barrier
	s_and_saveexec_b64 s[0:1], s[10:11]
	s_cbranch_execz .LBB0_1289
	v_mov_b32_e32 v0, 0x23fc0
	s_waitcnt vmcnt(0) expcnt(0) lgkmcnt(0)
	ds_read_b64 v[4:5], v0
	s_lshl_b32 s2, s19, 8
	s_add_u32 s2, s42, s2
	s_addc_u32 s3, s43, 0
	v_mov_b32_e32 v1, 0x1000
	v_mov_b32_e32 v2, 1
	global_atomic_add v1, v1, v2, s[2:3] offset:1024 sc0
	s_waitcnt lgkmcnt(0)
	v_readfirstlane_b32 s8, v4
	v_readfirstlane_b32 s9, v5
	s_mul_i32 s72, s8, 9
	s_mul_i32 s73, s9, 9
	s_waitcnt vmcnt(0)
	v_readfirstlane_b32 s74, v1
	s_add_i32 s74, s74, 1
	s_cmp_lg_u32 s74, s72
	s_cbranch_scc1 .Lgb8_poll
	buffer_wbl2 sc1
	s_waitcnt vmcnt(0)
	v_mov_b32_e32 v1, 0x3323000
	global_atomic_add v1, v2, s[44:45] offset:1024

.LBB0_1305:
	s_waitcnt vmcnt(0)
	s_barrier
	s_and_saveexec_b64 s[0:1], s[10:11]
	s_cbranch_execz .LBB0_1357
	v_mov_b32_e32 v0, 0x23fc0
	s_waitcnt vmcnt(0) expcnt(0) lgkmcnt(0)
	ds_read_b64 v[4:5], v0
	s_lshl_b32 s2, s19, 8
	s_add_u32 s2, s42, s2
	s_addc_u32 s3, s43, 0
	v_mov_b32_e32 v1, 0x1000
	v_mov_b32_e32 v2, 1
	global_atomic_add v1, v1, v2, s[2:3] offset:1024 sc0
	s_waitcnt lgkmcnt(0)
	v_readfirstlane_b32 s8, v4
	v_readfirstlane_b32 s9, v5
	s_mul_i32 s72, s8, 10
	s_mul_i32 s73, s9, 10
	s_waitcnt vmcnt(0)
	v_readfirstlane_b32 s74, v1
	s_add_i32 s74, s74, 1
	s_cmp_lg_u32 s74, s72
	s_cbranch_scc1 .Lgb9_poll
	buffer_wbl2 sc1
	s_waitcnt vmcnt(0)
	v_mov_b32_e32 v1, 0x3323000
	global_atomic_add v1, v2, s[44:45] offset:1024

.LBB0_1367:
	s_waitcnt vmcnt(0)
	s_barrier
	s_and_saveexec_b64 s[0:1], s[10:11]
	s_cbranch_execz .LBB0_1419
	v_mov_b32_e32 v0, 0x23fc0
	s_waitcnt vmcnt(0) expcnt(0) lgkmcnt(0)
	ds_read_b64 v[4:5], v0
	s_lshl_b32 s2, s19, 8
	s_add_u32 s2, s42, s2
	s_addc_u32 s3, s43, 0
	v_mov_b32_e32 v1, 0x1000
	v_mov_b32_e32 v2, 1
	global_atomic_add v1, v1, v2, s[2:3] offset:1024 sc0
	s_waitcnt lgkmcnt(0)
	v_readfirstlane_b32 s8, v4
	v_readfirstlane_b32 s9, v5
	s_mul_i32 s72, s8, 11
	s_mul_i32 s73, s9, 11
	s_waitcnt vmcnt(0)
	v_readfirstlane_b32 s74, v1
	s_add_i32 s74, s74, 1
	s_cmp_lg_u32 s74, s72
	s_cbranch_scc1 .Lgb10_poll
	buffer_wbl2 sc1
	s_waitcnt vmcnt(0)
	v_mov_b32_e32 v1, 0x3323000
	global_atomic_add v1, v2, s[44:45] offset:1024

.LBB0_1787:
	s_setprio 0
	s_waitcnt vmcnt(0)
	s_barrier
	s_and_saveexec_b64 s[0:1], s[10:11]
	s_cbranch_execz .LBB0_1839
	v_mov_b32_e32 v0, 0x23fc0
	s_waitcnt vmcnt(0) expcnt(0) lgkmcnt(0)
	ds_read_b64 v[4:5], v0
	s_lshl_b32 s2, s19, 8
	s_add_u32 s2, s42, s2
	s_addc_u32 s3, s43, 0
	v_mov_b32_e32 v1, 0x1000
	v_mov_b32_e32 v2, 1
	global_atomic_add v1, v1, v2, s[2:3] offset:1024 sc0
	s_waitcnt lgkmcnt(0)
	v_readfirstlane_b32 s8, v4
	v_readfirstlane_b32 s9, v5
	s_mul_i32 s72, s8, 12
	s_mul_i32 s73, s9, 12
	s_waitcnt vmcnt(0)
	v_readfirstlane_b32 s74, v1
	s_add_i32 s74, s74, 1
	s_cmp_lg_u32 s74, s72
	s_cbranch_scc1 .Lgb11_poll
	buffer_wbl2 sc1
	s_waitcnt vmcnt(0)
	v_mov_b32_e32 v1, 0x3323000
	global_atomic_add v1, v2, s[44:45] offset:1024

.LBB0_1867:
	s_waitcnt vmcnt(0)
	s_barrier
	s_and_saveexec_b64 s[0:1], s[10:11]
	s_cbranch_execz .LBB0_1919
	v_mov_b32_e32 v0, 0x23fc0
	s_waitcnt vmcnt(0) expcnt(0) lgkmcnt(0)
	ds_read_b64 v[4:5], v0
	s_lshl_b32 s2, s19, 8
	s_add_u32 s2, s42, s2
	s_addc_u32 s3, s43, 0
	v_mov_b32_e32 v1, 0x1000
	v_mov_b32_e32 v2, 1
	global_atomic_add v1, v1, v2, s[2:3] offset:1024 sc0
	s_waitcnt lgkmcnt(0)
	v_readfirstlane_b32 s8, v4
	v_readfirstlane_b32 s9, v5
	s_mul_i32 s72, s8, 13
	s_mul_i32 s73, s9, 13
	s_waitcnt vmcnt(0)
	v_readfirstlane_b32 s74, v1
	s_add_i32 s74, s74, 1
	s_cmp_lg_u32 s74, s72
	s_cbranch_scc1 .Lgb12_poll
	buffer_wbl2 sc1
	s_waitcnt vmcnt(0)
	v_mov_b32_e32 v1, 0x3323000
	global_atomic_add v1, v2, s[44:45] offset:1024

.LBB0_1943:
	s_waitcnt vmcnt(0)
	s_barrier
	s_and_saveexec_b64 s[0:1], s[10:11]
	s_cbranch_execz .LBB0_1995
	v_mov_b32_e32 v0, 0x23fc0
	s_waitcnt vmcnt(0) expcnt(0) lgkmcnt(0)
	ds_read_b64 v[4:5], v0
	s_lshl_b32 s2, s19, 8
	s_add_u32 s2, s42, s2
	s_addc_u32 s3, s43, 0
	v_mov_b32_e32 v1, 0x1000
	v_mov_b32_e32 v2, 1
	global_atomic_add v1, v1, v2, s[2:3] offset:1024 sc0
	s_waitcnt lgkmcnt(0)
	v_readfirstlane_b32 s8, v4
	v_readfirstlane_b32 s9, v5
	s_mul_i32 s72, s8, 14
	s_mul_i32 s73, s9, 14
	s_waitcnt vmcnt(0)
	v_readfirstlane_b32 s74, v1
	s_add_i32 s74, s74, 1
	s_cmp_lg_u32 s74, s72
	s_cbranch_scc1 .Lgb13_poll
	buffer_wbl2 sc1
	s_waitcnt vmcnt(0)
	v_mov_b32_e32 v1, 0x3323000
	global_atomic_add v1, v2, s[44:45] offset:1024
